# v38 plus the scan state-update permlane32_swap/DPP reductions and the double-buffered off-diagonal S^T chains (fewer LDS round trips)
# speedup vs baseline: 1.0151x; 1.0016x over previous
; #define LAS __attribute__((address_space(3)))
; #define MFMA32(a, b, c) __builtin_amdgcn_mfma_f32_32x32x16_bf16((a), (b), (c), 0, 0, 0)
; #define DOT2(a, b, c) dot2_bf16((a), (b), (c))
; DI bf16x8 pack_step(const f32x16& x, int s) { u32x4 p = {pk2(x[8 * s], x[8 * s + 1]), pk2(x[8 * s + 2], x[8 * s + 3]), pk2(x[8 * s + 4], x[8 * s + 5]), pk2(x[8 * s + 6], x[8 * s + 7])}; return __builtin_bit_cast(bf16x8, p); }
; DI bf16x8 ldsfrag(const LAS unsigned char* buf, unsigned o) { const s16x4 lo = *(const LAS s16x4*)(buf + o), hi = *(const LAS s16x4*)(buf + (o ^ 16u)); return __builtin_shufflevector(lo, hi, 0, 1, 2, 3, 4, 5, 6, 7); }
; DI void scan_phase(const Args& A, LAS unsigned char* lds, int wv) {
;     ...
;             for (int tb = 0; tb < 2; ++tb) {
;                 __builtin_amdgcn_sched_barrier(0);
;                 const unsigned qo = qro + tb * 8192u;
;                 f32x16 ha;
; #pragma unroll
;                 for (int i = 0; i < 16; ++i) ha[i] = 0.f;
;                 float qnv = 0.f;
; #pragma unroll
;                 for (int kk = 0; kk < 8; ++kk) {
;                     const bf16x8 qa = ldsfrag(Qb, qo + (((2u * kk) ^ xr) << 4));
;                     ha = MFMA32(qa, pack_step(cacc[kk >> 1], kk & 1), ha);
;                     { const u32x2 nb0 = *(const LAS u32x2*)(nbh + 8 * kk), nb1 = *(const LAS u32x2*)(nbh + 8 * kk + 4); const u32x4 qw = __builtin_bit_cast(u32x4, qa);
;                       qnv = DOT2(qw.x, nb0.x, qnv); qnv = DOT2(qw.y, nb0.y, qnv); qnv = DOT2(qw.z, nb1.x, qnv); qnv = DOT2(qw.w, nb1.y, qnv); }
;                 }
;                 qnv += __shfl_xor(qnv, 32);
; #pragma unroll
;                 for (int g = 0; g < 4; ++g) { const f32x4 av = *(const LAS f32x4*)(wh + 128 + 32 * tb + 8 * g);
; #pragma unroll
;                     for (int q = 0; q < 4; ++q) ha[4 * g + q] *= av[q]; }
.LBB0_1229:
	s_or_b64 exec, exec, s[6:7]
	v_xor_b32_e32 v65, 63, v192
	v_cndmask_b32_e64 v175, v65, v192, s[4:5]
	v_xor_b32_e32 v65, 32, v151
	s_bitcmp1_b32 s80, 0
	s_waitcnt lgkmcnt(0)
	v_cmp_lt_i32_e32 vcc, v65, v64
	s_cselect_b32 s6, 0xc000, 0
	v_lshlrev_b32_e32 v92, 4, v172
	v_cndmask_b32_e32 v64, v151, v65, vcc
	v_lshl_add_u32 v174, v192, 2, s47
	v_lshl_or_b32 v193, v164, 8, v144
	v_lshl_add_u32 v168, v164, 2, s47
	s_add_i32 s10, s6, 0
	v_and_b32_e32 v194, 0xf0, v92
	v_lshlrev_b32_e32 v169, 2, v64
	v_add_u32_e32 v84, s47, v144
	v_or_b32_e32 v64, v193, v194
	v_add_u32_e32 v176, s10, v64
	v_bitop3_b32 v64, v193, 16, v194 bitop3:0x36
	v_add_u32_e32 v177, s10, v64
	ds_read_b64 v[80:81], v176
	ds_read_b64 v[82:83], v177
	v_add_u32_e32 v170, 0x800, v84
	ds_read2_b64 v[84:87], v170 offset1:2
	ds_read2_b64 v[88:91], v170 offset0:4 offset1:6
	v_mov_b32_e32 v147, v145
	s_waitcnt lgkmcnt(0)
	v_dot2c_f32_bf16 v147, v80, v84
	v_cvt_pk_bf16_f32 v112, v0, v1
	v_cvt_pk_bf16_f32 v113, v2, v3
	v_cvt_pk_bf16_f32 v114, v4, v5
	v_cvt_pk_bf16_f32 v115, v6, v7
	v_dot2c_f32_bf16 v147, v81, v85
	v_bitop3_b32 v195, v92, 32, v157 bitop3:0x6c
	v_dot2c_f32_bf16 v147, v82, v86
	v_cvt_pk_bf16_f32 v116, v8, v9
	v_mfma_f32_32x32x16_bf16 v[64:79], v[80:83], v[112:115], 0
	v_or_b32_e32 v80, v193, v195
	v_bitop3_b32 v82, v193, 16, v195 bitop3:0x36
	v_add_u32_e32 v190, s10, v80
	v_add_u32_e32 v191, s10, v82
	v_dot2c_f32_bf16 v147, v83, v87
	ds_read_b64 v[80:81], v190
	ds_read_b64 v[82:83], v191
	s_waitcnt lgkmcnt(0)
	v_dot2c_f32_bf16 v147, v80, v88
	v_cvt_pk_bf16_f32 v117, v10, v11
	v_cvt_pk_bf16_f32 v118, v12, v13
	v_cvt_pk_bf16_f32 v119, v14, v15
	v_dot2c_f32_bf16 v147, v81, v89
	v_bitop3_b32 v196, v92, 64, v157 bitop3:0x6c
	v_dot2c_f32_bf16 v147, v82, v90
	ds_read2_b64 v[84:87], v170 offset0:8 offset1:10
	v_mfma_f32_32x32x16_bf16 v[64:79], v[80:83], v[116:119], v[64:79]
	v_or_b32_e32 v80, v193, v196
	v_bitop3_b32 v82, v193, 16, v196 bitop3:0x36
	v_add_u32_e32 v188, s10, v80
	v_add_u32_e32 v189, s10, v82
	v_dot2c_f32_bf16 v147, v83, v91
	ds_read_b64 v[80:81], v188
	ds_read_b64 v[82:83], v189
	s_waitcnt lgkmcnt(0)
	v_dot2c_f32_bf16 v147, v80, v84
	v_cvt_pk_bf16_f32 v120, v16, v17
	v_cvt_pk_bf16_f32 v121, v18, v19
	v_cvt_pk_bf16_f32 v122, v20, v21
	v_cvt_pk_bf16_f32 v123, v22, v23
	v_dot2c_f32_bf16 v147, v81, v85
	v_bitop3_b32 v197, v92, s16, v157 bitop3:0x6c
	v_dot2c_f32_bf16 v147, v82, v86
	s_movk_i32 s6, 0x80
	v_mfma_f32_32x32x16_bf16 v[64:79], v[80:83], v[120:123], v[64:79]
	v_or_b32_e32 v80, v193, v197
	v_bitop3_b32 v82, v193, 16, v197 bitop3:0x36
	v_add_u32_e32 v186, s10, v80
	v_add_u32_e32 v187, s10, v82
	v_dot2c_f32_bf16 v147, v83, v87
	ds_read_b64 v[80:81], v186
	ds_read_b64 v[82:83], v187
	ds_read2_b64 v[84:87], v170 offset0:12 offset1:14
	s_waitcnt lgkmcnt(0)
	v_dot2c_f32_bf16 v147, v80, v84
	v_cvt_pk_bf16_f32 v124, v24, v25
	v_cvt_pk_bf16_f32 v125, v26, v27
	v_cvt_pk_bf16_f32 v126, v28, v29
	v_cvt_pk_bf16_f32 v127, v30, v31
	v_dot2c_f32_bf16 v147, v81, v85
	v_bitop3_b32 v198, v92, s6, v157 bitop3:0x6c
	v_dot2c_f32_bf16 v147, v82, v86
	s_movk_i32 s6, 0xa0
	v_mfma_f32_32x32x16_bf16 v[64:79], v[80:83], v[124:127], v[64:79]
	v_or_b32_e32 v80, v193, v198
	v_bitop3_b32 v82, v193, 16, v198 bitop3:0x36
	v_add_u32_e32 v184, s10, v80
	v_add_u32_e32 v185, s10, v82
	v_dot2c_f32_bf16 v147, v83, v87
	ds_read_b64 v[80:81], v184
	ds_read_b64 v[82:83], v185
	ds_read2_b64 v[84:87], v170 offset0:16 offset1:18
	s_waitcnt lgkmcnt(0)
	v_dot2c_f32_bf16 v147, v80, v84
	v_cvt_pk_bf16_f32 v128, v32, v33
	v_cvt_pk_bf16_f32 v129, v34, v35
	v_cvt_pk_bf16_f32 v130, v36, v37
	v_cvt_pk_bf16_f32 v131, v38, v39
	v_dot2c_f32_bf16 v147, v81, v85
	v_bitop3_b32 v199, v92, s6, v157 bitop3:0x6c
	v_dot2c_f32_bf16 v147, v82, v86
	s_movk_i32 s6, 0xc0
	v_mfma_f32_32x32x16_bf16 v[64:79], v[80:83], v[128:131], v[64:79]
	v_or_b32_e32 v80, v193, v199
	v_bitop3_b32 v82, v193, 16, v199 bitop3:0x36
	v_add_u32_e32 v182, s10, v80
	v_add_u32_e32 v183, s10, v82
	v_dot2c_f32_bf16 v147, v83, v87
	ds_read_b64 v[80:81], v182
	ds_read_b64 v[82:83], v183
	ds_read2_b64 v[84:87], v170 offset0:20 offset1:22
	s_waitcnt lgkmcnt(0)
	v_dot2c_f32_bf16 v147, v80, v84
	v_cvt_pk_bf16_f32 v132, v40, v41
	v_cvt_pk_bf16_f32 v133, v42, v43
	v_cvt_pk_bf16_f32 v134, v44, v45
	v_cvt_pk_bf16_f32 v135, v46, v47
	v_dot2c_f32_bf16 v147, v81, v85
	v_bitop3_b32 v200, v92, s6, v157 bitop3:0x6c
	v_dot2c_f32_bf16 v147, v82, v86
	s_movk_i32 s6, 0xe0
	v_mfma_f32_32x32x16_bf16 v[64:79], v[80:83], v[132:135], v[64:79]
	v_or_b32_e32 v80, v193, v200
	v_bitop3_b32 v82, v193, 16, v200 bitop3:0x36
	v_add_u32_e32 v180, s10, v80
	v_add_u32_e32 v181, s10, v82
	v_dot2c_f32_bf16 v147, v83, v87
	ds_read_b64 v[80:81], v180
	ds_read_b64 v[82:83], v181
	ds_read2_b64 v[84:87], v170 offset0:24 offset1:26
	s_waitcnt lgkmcnt(0)
	v_dot2c_f32_bf16 v147, v80, v84
	v_cvt_pk_bf16_f32 v136, v48, v49
	v_cvt_pk_bf16_f32 v137, v50, v51
	v_cvt_pk_bf16_f32 v138, v52, v53
	v_cvt_pk_bf16_f32 v139, v54, v55
	v_dot2c_f32_bf16 v147, v81, v85
	v_bitop3_b32 v201, v92, s6, v157 bitop3:0x6c
	v_dot2c_f32_bf16 v147, v82, v86
	v_cvt_pk_bf16_f32 v140, v56, v57
	v_mfma_f32_32x32x16_bf16 v[64:79], v[80:83], v[136:139], v[64:79]
	v_or_b32_e32 v80, v193, v201
	v_bitop3_b32 v82, v193, 16, v201 bitop3:0x36
	v_add_u32_e32 v178, s10, v80
	v_add_u32_e32 v179, s10, v82
	v_dot2c_f32_bf16 v147, v83, v87
	ds_read_b64 v[80:81], v178
	ds_read_b64 v[82:83], v179
	v_cvt_pk_bf16_f32 v141, v58, v59
	v_cvt_pk_bf16_f32 v142, v60, v61
	v_cvt_pk_bf16_f32 v143, v62, v63
	ds_read2_b64 v[84:87], v170 offset0:28 offset1:30
	s_waitcnt lgkmcnt(0)
; #define LAS __attribute__((address_space(3)))
; #define MFMA32(a, b, c) __builtin_amdgcn_mfma_f32_32x32x16_bf16((a), (b), (c), 0, 0, 0)
; DI bf16x8 pack_step(const f32x16& x, int s) { u32x4 p = {pk2(x[8 * s], x[8 * s + 1]), pk2(x[8 * s + 2], x[8 * s + 3]), pk2(x[8 * s + 4], x[8 * s + 5]), pk2(x[8 * s + 6], x[8 * s + 7])}; return __builtin_bit_cast(bf16x8, p); }
; DI bf16x8 ldsfrag(const LAS unsigned char* buf, unsigned o) { const s16x4 lo = *(const LAS s16x4*)(buf + o), hi = *(const LAS s16x4*)(buf + (o ^ 16u)); return __builtin_shufflevector(lo, hi, 0, 1, 2, 3, 4, 5, 6, 7); }
; DI void scan_phase(const Args& A, LAS unsigned char* lds, int wv) {
;     ...
;                 qnv += __shfl_xor(qnv, 32);
; #pragma unroll
;                 for (int g = 0; g < 4; ++g) { const f32x4 av = *(const LAS f32x4*)(wh + 128 + 32 * tb + 8 * g);
; #pragma unroll
;                     for (int q = 0; q < 4; ++q) ha[4 * g + q] *= av[q]; }
;                 const float pmt = wr[64 + 32 * tb];
;                 const int tp = dir ? (63 - 32 * tb) - rj : 32 * tb + rj;
;                 float ds = 0.f;
; #pragma unroll
;                 for (int sb = 0; sb < 2; ++sb) {
;                     __builtin_amdgcn_sched_barrier(0);
;                     if (sb != tb && (dir ? sb < tb : sb > tb)) continue;
;                     const unsigned ko = qro + sb * 8192u;
;                     f32x16 st;
; #pragma unroll
;                     for (int i = 0; i < 16; ++i) st[i] = 0.f;
; #pragma unroll
;                     for (int kk = 0; kk < 8; ++kk) { const unsigned c = ((2u * kk) ^ xr) << 4; st = MFMA32(ldsfrag(Kb, ko + c), ldsfrag(Qb, qo + c), st); }
; #pragma unroll
;                     for (int g = 0; g < 4; ++g) { const f32x4 uv = *(const LAS f32x4*)(wh + 32 * sb + 8 * g);
; #pragma unroll
;                         for (int q = 0; q < 4; ++q) {
;                             const int sc = 32 * sb + q + 8 * g;
;                             const int sp = sbase + sgn * sc;
;                             st[4 * g + q] *= __builtin_amdgcn_exp2f((sp <= tp) ? uv[q] - pmt : -1e30f);
;                             ds += st[4 * g + q];
;                         } }
;                     ha = MFMA32(pack_step(st, 0), vf[2 * sb], ha);
;                     ha = MFMA32(pack_step(st, 1), vf[2 * sb + 1], ha);
	v_dot2c_f32_bf16 v147, v80, v84
	v_mfma_f32_32x32x16_bf16 v[64:79], v[80:83], v[140:143], v[64:79]
	v_dot2c_f32_bf16 v147, v81, v85
	s_nop 0
	v_dot2c_f32_bf16 v147, v82, v86
	s_nop 0
	v_dot2c_f32_bf16 v147, v83, v87
	ds_read_b128 v[80:83], v174 offset:512
	ds_read_b128 v[84:87], v174 offset:544
	ds_read_b128 v[88:91], v174 offset:576
	ds_read_b128 v[92:95], v174 offset:608
	ds_bpermute_b32 v149, v169, v147
	ds_read_b32 v148, v168 offset:256
	s_waitcnt lgkmcnt(0)
	s_nop 2
	v_pk_mul_f32 v[64:65], v[64:65], v[80:81]
	v_xor_b32_e32 v80, 63, v164
	v_cndmask_b32_e64 v80, v80, v164, s[4:5]
	v_pk_mul_f32 v[78:79], v[78:79], v[94:95]
	v_pk_mul_f32 v[76:77], v[76:77], v[92:93]
	v_pk_mul_f32 v[74:75], v[74:75], v[90:91]
	v_pk_mul_f32 v[72:73], v[72:73], v[88:89]
	v_pk_mul_f32 v[70:71], v[70:71], v[86:87]
	v_pk_mul_f32 v[68:69], v[68:69], v[84:85]
	v_pk_mul_f32 v[66:67], v[66:67], v[82:83]
	v_sub_u32_e32 v202, v80, v175
	ds_read_b64 v[204:205], v176
	ds_read_b64 v[206:207], v177
	ds_read_b64 v[212:213], v176 offset:16384
	ds_read_b64 v[214:215], v177 offset:16384
	ds_read_b64 v[252:253], v190
	ds_read_b64 v[254:255], v191
	ds_read_b64 v[248:249], v190 offset:16384
	ds_read_b64 v[250:251], v191 offset:16384
	v_cmp_lt_i32_e32 vcc, -1, v202
	s_waitcnt lgkmcnt(4)
	v_mfma_f32_32x32x16_bf16 v[80:95], v[212:215], v[204:207], 0
	ds_read_b64 v[204:205], v188
	ds_read_b64 v[206:207], v189
	ds_read_b64 v[212:213], v188 offset:16384
	ds_read_b64 v[214:215], v189 offset:16384
	s_waitcnt lgkmcnt(4)
	v_mfma_f32_32x32x16_bf16 v[80:95], v[248:251], v[252:255], v[80:95]
	ds_read_b64 v[252:253], v186
	ds_read_b64 v[254:255], v187
	ds_read_b64 v[248:249], v186 offset:16384
	ds_read_b64 v[250:251], v187 offset:16384
	s_waitcnt lgkmcnt(4)
	v_mfma_f32_32x32x16_bf16 v[80:95], v[212:215], v[204:207], v[80:95]
	ds_read_b64 v[204:205], v184
	ds_read_b64 v[206:207], v185
	ds_read_b64 v[212:213], v184 offset:16384
	ds_read_b64 v[214:215], v185 offset:16384
	s_waitcnt lgkmcnt(4)
	v_mfma_f32_32x32x16_bf16 v[80:95], v[248:251], v[252:255], v[80:95]
	ds_read_b64 v[252:253], v182
	ds_read_b64 v[254:255], v183
	ds_read_b64 v[248:249], v182 offset:16384
	ds_read_b64 v[250:251], v183 offset:16384
	s_waitcnt lgkmcnt(4)
	v_mfma_f32_32x32x16_bf16 v[80:95], v[212:215], v[204:207], v[80:95]
	ds_read_b64 v[204:205], v180
	ds_read_b64 v[206:207], v181
	ds_read_b64 v[212:213], v180 offset:16384
	ds_read_b64 v[214:215], v181 offset:16384
	s_waitcnt lgkmcnt(4)
	v_mfma_f32_32x32x16_bf16 v[80:95], v[248:251], v[252:255], v[80:95]
	ds_read_b64 v[252:253], v178
	ds_read_b64 v[254:255], v179
	ds_read_b64 v[248:249], v178 offset:16384
	ds_read_b64 v[250:251], v179 offset:16384
	s_waitcnt lgkmcnt(4)
	v_mfma_f32_32x32x16_bf16 v[80:95], v[212:215], v[204:207], v[80:95]
	s_waitcnt lgkmcnt(0)
	v_mfma_f32_32x32x16_bf16 v[80:95], v[248:251], v[252:255], v[80:95]
	ds_read_b128 v[204:207], v174
	ds_read_b128 v[208:211], v174 offset:32
	s_waitcnt lgkmcnt(0)
	v_sub_f32_e32 v146, v204, v148
	v_cndmask_b32_e32 v146, v158, v146, vcc
	v_exp_f32_e32 v204, v146
	v_sub_f32_e32 v146, v205, v148
	v_cmp_le_i32_e32 vcc, s46, v202
	v_sub_f32_e32 v203, v206, v148
	s_nop 0
	v_cndmask_b32_e32 v146, v158, v146, vcc
	v_exp_f32_e32 v205, v146
	v_cmp_le_i32_e32 vcc, s0, v202
	v_pk_mul_f32 v[80:81], v[80:81], v[204:205]
	s_nop 0
	v_cndmask_b32_e32 v203, v158, v203, vcc
	v_exp_f32_e32 v204, v203
	v_sub_f32_e32 v203, v207, v148
	v_cmp_le_i32_e32 vcc, s1, v202
	v_add_f32_e32 v146, 0, v80
	v_add_f32_e32 v146, v81, v146
	v_cndmask_b32_e32 v203, v158, v203, vcc
	v_exp_f32_e32 v205, v203
	v_sub_f32_e32 v203, v208, v148
	v_cmp_le_i32_e32 vcc, s93, v202
	v_cvt_pk_bf16_f32 v80, v80, v81
	v_pk_mul_f32 v[82:83], v[82:83], v[204:205]
	v_cndmask_b32_e32 v203, v158, v203, vcc
	v_exp_f32_e32 v204, v203
	v_sub_f32_e32 v203, v209, v148
	v_cmp_le_i32_e32 vcc, s54, v202
	v_add_f32_e32 v146, v82, v146
	v_add_f32_e32 v146, v83, v146
	v_cndmask_b32_e32 v203, v158, v203, vcc
	v_exp_f32_e32 v205, v203
	v_sub_f32_e32 v203, v210, v148
	v_cmp_le_i32_e32 vcc, s30, v202
	v_cvt_pk_bf16_f32 v81, v82, v83
	v_pk_mul_f32 v[84:85], v[84:85], v[204:205]
	v_cndmask_b32_e32 v203, v158, v203, vcc
	v_exp_f32_e32 v204, v203
	v_sub_f32_e32 v203, v211, v148
	v_cmp_le_i32_e32 vcc, s31, v202
	v_add_f32_e32 v146, v84, v146
	v_add_f32_e32 v146, v85, v146
	v_cndmask_b32_e32 v203, v158, v203, vcc
	v_exp_f32_e32 v205, v203
	v_cmp_le_i32_e32 vcc, s55, v202
	v_cvt_pk_bf16_f32 v82, v84, v85
	v_pk_mul_f32 v[86:87], v[86:87], v[204:205]
	ds_read_b128 v[204:207], v174 offset:64
	v_add_f32_e32 v146, v86, v146
	v_add_f32_e32 v146, v87, v146
	v_cvt_pk_bf16_f32 v83, v86, v87
	s_waitcnt lgkmcnt(0)
	v_sub_f32_e32 v203, v204, v148
	v_cndmask_b32_e32 v203, v158, v203, vcc
	v_exp_f32_e32 v204, v203
	v_sub_f32_e32 v203, v205, v148
	v_cmp_le_i32_e32 vcc, s34, v202
	s_waitcnt vmcnt(0)
	v_mfma_f32_32x32x16_bf16 v[64:79], v[80:83], v[108:111], v[64:79]
	v_cndmask_b32_e32 v203, v158, v203, vcc
	v_exp_f32_e32 v205, v203
	v_cmp_le_i32_e32 vcc, s97, v202
	v_pk_mul_f32 v[204:205], v[88:89], v[204:205]
	s_nop 0
	v_add_f32_e32 v88, v204, v146
	v_add_f32_e32 v146, v205, v88
	v_sub_f32_e32 v88, v206, v148
	v_cndmask_b32_e32 v88, v158, v88, vcc
	v_sub_f32_e32 v89, v207, v148
	v_cmp_le_i32_e32 vcc, s52, v202
	v_exp_f32_e32 v88, v88
	v_cvt_pk_bf16_f32 v80, v204, v205
	v_cndmask_b32_e32 v89, v158, v89, vcc
	v_exp_f32_e32 v89, v89
	v_cmp_le_i32_e32 vcc, s60, v202
	v_pk_mul_f32 v[206:207], v[90:91], v[88:89]
	s_nop 0
	v_add_f32_e32 v88, v206, v146
	v_add_f32_e32 v146, v207, v88
	ds_read_b128 v[88:91], v174 offset:96
	v_cvt_pk_bf16_f32 v81, v206, v207
	s_waitcnt lgkmcnt(0)
	v_sub_f32_e32 v88, v88, v148
	v_cndmask_b32_e32 v88, v158, v88, vcc
	v_sub_f32_e32 v89, v89, v148
	v_cmp_le_i32_e32 vcc, s35, v202
	v_sub_f32_e32 v90, v90, v148
	v_sub_f32_e32 v91, v91, v148
	v_cndmask_b32_e32 v89, v158, v89, vcc
	v_cmp_le_i32_e32 vcc, s56, v202
	v_exp_f32_e32 v88, v88
	v_exp_f32_e32 v89, v89
	v_cndmask_b32_e32 v90, v158, v90, vcc
	v_cmp_le_i32_e32 vcc, s92, v202
	v_exp_f32_e32 v90, v90
	v_pk_mul_f32 v[88:89], v[92:93], v[88:89]
	v_cndmask_b32_e32 v91, v158, v91, vcc
	v_exp_f32_e32 v91, v91
	v_cvt_pk_bf16_f32 v82, v88, v89
	v_add_f32_e32 v92, v88, v146
	v_add_f32_e32 v92, v89, v92
	v_pk_mul_f32 v[90:91], v[94:95], v[90:91]
	s_nop 0
	v_cvt_pk_bf16_f32 v83, v90, v91
	v_add_f32_e32 v92, v90, v92
	v_add_f32_e32 v146, v91, v92
	v_mfma_f32_32x32x16_bf16 v[64:79], v[80:83], v[104:107], v[64:79]
	s_andn2_b64 vcc, exec, s[22:23]
	v_or_b32_e32 v203, 0x2000, v193
	s_cbranch_vccnz .LBB0_1231
; #define LAS __attribute__((address_space(3)))
; #define MFMA32(a, b, c) __builtin_amdgcn_mfma_f32_32x32x16_bf16((a), (b), (c), 0, 0, 0)
; DI bf16x8 pack_step(const f32x16& x, int s) { u32x4 p = {pk2(x[8 * s], x[8 * s + 1]), pk2(x[8 * s + 2], x[8 * s + 3]), pk2(x[8 * s + 4], x[8 * s + 5]), pk2(x[8 * s + 6], x[8 * s + 7])}; return __builtin_bit_cast(bf16x8, p); }
; DI bf16x8 ldsfrag(const LAS unsigned char* buf, unsigned o) { const s16x4 lo = *(const LAS s16x4*)(buf + o), hi = *(const LAS s16x4*)(buf + (o ^ 16u)); return __builtin_shufflevector(lo, hi, 0, 1, 2, 3, 4, 5, 6, 7); }
; DI void scan_phase(const Args& A, LAS unsigned char* lds, int wv) {
;     ...
;                 for (int sb = 0; sb < 2; ++sb) {
;                     __builtin_amdgcn_sched_barrier(0);
;                     if (sb != tb && (dir ? sb < tb : sb > tb)) continue;
;                     const unsigned ko = qro + sb * 8192u;
;                     f32x16 st;
; #pragma unroll
;                     for (int i = 0; i < 16; ++i) st[i] = 0.f;
; #pragma unroll
;                     for (int kk = 0; kk < 8; ++kk) { const unsigned c = ((2u * kk) ^ xr) << 4; st = MFMA32(ldsfrag(Kb, ko + c), ldsfrag(Qb, qo + c), st); }
; #pragma unroll
;                     for (int g = 0; g < 4; ++g) { const f32x4 uv = *(const LAS f32x4*)(wh + 32 * sb + 8 * g);
; #pragma unroll
;                         for (int q = 0; q < 4; ++q) {
;                             const int sc = 32 * sb + q + 8 * g;
;                             const int sp = sbase + sgn * sc;
;                             st[4 * g + q] *= __builtin_amdgcn_exp2f((sp <= tp) ? uv[q] - pmt : -1e30f);
;                             ds += st[4 * g + q];
;                         } }
;                     ha = MFMA32(pack_step(st, 0), vf[2 * sb], ha);
;                     ha = MFMA32(pack_step(st, 1), vf[2 * sb + 1], ha);
	v_add3_u32 v80, v193, v194, s10
	ds_read_b64 v[80:81], v80 offset:24576
	v_or_b32_e32 v82, v203, v194
	v_xad_u32 v82, v82, 16, s10
	ds_read_b64 v[82:83], v82 offset:16384
	ds_read_b64 v[84:85], v176
	ds_read_b64 v[86:87], v177
	v_add3_u32 v204, v193, v195, s10
	ds_read_b64 v[204:205], v204 offset:24576
	v_or_b32_e32 v206, v203, v195
	v_xad_u32 v206, v206, 16, s10
	ds_read_b64 v[206:207], v206 offset:16384
	ds_read_b64 v[208:209], v190
	ds_read_b64 v[210:211], v191
	s_waitcnt lgkmcnt(4)
	v_mfma_f32_32x32x16_bf16 v[80:95], v[80:83], v[84:87], 0
	v_add3_u32 v248, v193, v196, s10
	ds_read_b64 v[248:249], v248 offset:24576
	v_or_b32_e32 v250, v203, v196
	v_xad_u32 v250, v250, 16, s10
	ds_read_b64 v[250:251], v250 offset:16384
	ds_read_b64 v[252:253], v188
	ds_read_b64 v[254:255], v189
	s_movk_i32 s6, 0xffdf
	v_cmp_lt_i32_e32 vcc, s6, v202
	s_movk_i32 s6, 0xffde
	s_waitcnt lgkmcnt(4)
	v_mfma_f32_32x32x16_bf16 v[80:95], v[204:207], v[208:211], v[80:95]
	v_add3_u32 v204, v193, v197, s10
	ds_read_b64 v[204:205], v204 offset:24576
	v_or_b32_e32 v206, v203, v197
	v_xad_u32 v206, v206, 16, s10
	ds_read_b64 v[206:207], v206 offset:16384
	ds_read_b64 v[208:209], v186
	ds_read_b64 v[210:211], v187
	s_waitcnt lgkmcnt(4)
	v_mfma_f32_32x32x16_bf16 v[80:95], v[248:251], v[252:255], v[80:95]
	v_add3_u32 v248, v193, v198, s10
	ds_read_b64 v[248:249], v248 offset:24576
	v_or_b32_e32 v250, v203, v198
	v_xad_u32 v250, v250, 16, s10
	ds_read_b64 v[250:251], v250 offset:16384
	ds_read_b64 v[252:253], v184
	ds_read_b64 v[254:255], v185
	s_waitcnt lgkmcnt(4)
	v_mfma_f32_32x32x16_bf16 v[80:95], v[204:207], v[208:211], v[80:95]
	v_add3_u32 v204, v193, v199, s10
	ds_read_b64 v[204:205], v204 offset:24576
	v_or_b32_e32 v206, v203, v199
	v_xad_u32 v206, v206, 16, s10
	ds_read_b64 v[206:207], v206 offset:16384
	ds_read_b64 v[208:209], v182
	ds_read_b64 v[210:211], v183
	s_waitcnt lgkmcnt(4)
	v_mfma_f32_32x32x16_bf16 v[80:95], v[248:251], v[252:255], v[80:95]
	v_add3_u32 v248, v193, v200, s10
	ds_read_b64 v[248:249], v248 offset:24576
	v_or_b32_e32 v250, v203, v200
	v_xad_u32 v250, v250, 16, s10
	ds_read_b64 v[250:251], v250 offset:16384
	ds_read_b64 v[252:253], v180
	ds_read_b64 v[254:255], v181
	s_waitcnt lgkmcnt(4)
	v_mfma_f32_32x32x16_bf16 v[80:95], v[204:207], v[208:211], v[80:95]
	v_add3_u32 v204, v193, v201, s10
	ds_read_b64 v[204:205], v204 offset:24576
	v_or_b32_e32 v206, v203, v201
	v_xad_u32 v206, v206, 16, s10
	ds_read_b64 v[206:207], v206 offset:16384
	ds_read_b64 v[208:209], v178
	ds_read_b64 v[210:211], v179
	s_waitcnt lgkmcnt(4)
	v_mfma_f32_32x32x16_bf16 v[80:95], v[248:251], v[252:255], v[80:95]
	s_waitcnt lgkmcnt(0)
	v_mfma_f32_32x32x16_bf16 v[80:95], v[204:207], v[208:211], v[80:95]
	ds_read_b128 v[204:207], v174 offset:128
	ds_read_b128 v[208:211], v174 offset:160
	s_waitcnt lgkmcnt(1)
	v_sub_f32_e32 v204, v204, v148
	v_cndmask_b32_e32 v204, v158, v204, vcc
	v_sub_f32_e32 v205, v205, v148
	v_cmp_lt_i32_e32 vcc, s6, v202
	v_exp_f32_e32 v204, v204
	s_movk_i32 s6, 0xffdd
	v_cndmask_b32_e32 v205, v158, v205, vcc
	v_exp_f32_e32 v205, v205
	v_cmp_lt_i32_e32 vcc, s6, v202
	s_movk_i32 s6, 0xffdc
	v_pk_mul_f32 v[80:81], v[80:81], v[204:205]
	v_sub_f32_e32 v204, v206, v148
	v_cndmask_b32_e32 v204, v158, v204, vcc
	v_sub_f32_e32 v205, v207, v148
	v_cmp_lt_i32_e32 vcc, s6, v202
	v_exp_f32_e32 v204, v204
	s_movk_i32 s6, 0xffd7
	v_cndmask_b32_e32 v205, v158, v205, vcc
	v_exp_f32_e32 v205, v205
	v_cmp_lt_i32_e32 vcc, s6, v202
	s_movk_i32 s6, 0xffd6
	v_add_f32_e32 v146, v146, v80
	v_pk_mul_f32 v[82:83], v[82:83], v[204:205]
	s_waitcnt lgkmcnt(0)
	v_sub_f32_e32 v204, v208, v148
	v_cndmask_b32_e32 v204, v158, v204, vcc
	v_sub_f32_e32 v205, v209, v148
	v_cmp_lt_i32_e32 vcc, s6, v202
	v_exp_f32_e32 v204, v204
	s_movk_i32 s6, 0xffd5
	v_cndmask_b32_e32 v205, v158, v205, vcc
	v_exp_f32_e32 v205, v205
	v_cmp_lt_i32_e32 vcc, s6, v202
	s_movk_i32 s6, 0xffd4
	v_add_f32_e32 v146, v81, v146
	v_pk_mul_f32 v[84:85], v[84:85], v[204:205]
	v_sub_f32_e32 v204, v210, v148
	v_cndmask_b32_e32 v204, v158, v204, vcc
	v_sub_f32_e32 v205, v211, v148
	v_cmp_lt_i32_e32 vcc, s6, v202
	v_exp_f32_e32 v204, v204
	s_movk_i32 s6, 0xffcf
	v_cndmask_b32_e32 v205, v158, v205, vcc
	v_exp_f32_e32 v205, v205
	v_cmp_lt_i32_e32 vcc, s6, v202
	s_movk_i32 s6, 0xffce
	v_add_f32_e32 v146, v82, v146
	v_pk_mul_f32 v[86:87], v[86:87], v[204:205]
	ds_read_b128 v[204:207], v174 offset:192
	v_add_f32_e32 v146, v83, v146
	v_cvt_pk_bf16_f32 v80, v80, v81
	v_cvt_pk_bf16_f32 v81, v82, v83
	v_cvt_pk_bf16_f32 v82, v84, v85
	s_waitcnt lgkmcnt(0)
	v_sub_f32_e32 v204, v204, v148
	v_cndmask_b32_e32 v204, v158, v204, vcc
	v_sub_f32_e32 v205, v205, v148
	v_cmp_lt_i32_e32 vcc, s6, v202
	v_exp_f32_e32 v204, v204
	s_movk_i32 s6, 0xffcd
	v_cndmask_b32_e32 v205, v158, v205, vcc
	v_exp_f32_e32 v205, v205
	v_cmp_lt_i32_e32 vcc, s6, v202
	s_movk_i32 s6, 0xffcc
	v_cvt_pk_bf16_f32 v83, v86, v87
	v_pk_mul_f32 v[88:89], v[88:89], v[204:205]
	v_sub_f32_e32 v204, v206, v148
	v_cndmask_b32_e32 v204, v158, v204, vcc
	v_sub_f32_e32 v205, v207, v148
	v_cmp_lt_i32_e32 vcc, s6, v202
	v_exp_f32_e32 v204, v204
	s_movk_i32 s6, 0xffc7
	v_cndmask_b32_e32 v205, v158, v205, vcc
	v_exp_f32_e32 v205, v205
	v_cmp_lt_i32_e32 vcc, s6, v202
	s_movk_i32 s6, 0xffc6
	v_mfma_f32_32x32x16_bf16 v[64:79], v[80:83], v[100:103], v[64:79]
	v_mul_f32_e64 v90, v90, v204
	v_mul_f32_e64 v91, v91, v205
	ds_read_b128 v[204:207], v174 offset:224
	v_cvt_pk_bf16_f32 v80, v88, v89
	v_cvt_pk_bf16_f32 v81, v90, v91
	v_add_f32_e32 v146, v84, v146
	v_add_f32_e32 v146, v85, v146
	s_waitcnt lgkmcnt(0)
	v_sub_f32_e32 v204, v204, v148
	v_cndmask_b32_e32 v204, v158, v204, vcc
	v_sub_f32_e32 v205, v205, v148
	v_cmp_lt_i32_e32 vcc, s6, v202
	v_exp_f32_e32 v204, v204
	s_movk_i32 s6, 0xffc5
	v_cndmask_b32_e32 v205, v158, v205, vcc
	v_exp_f32_e32 v205, v205
	v_cmp_lt_i32_e32 vcc, s6, v202
	s_movk_i32 s6, 0xffc4
	v_add_f32_e32 v146, v86, v146
	v_pk_mul_f32 v[92:93], v[92:93], v[204:205]
	v_sub_f32_e32 v204, v206, v148
	v_cndmask_b32_e32 v204, v158, v204, vcc
	v_sub_f32_e32 v148, v207, v148
	v_cmp_lt_i32_e32 vcc, s6, v202
	v_exp_f32_e32 v204, v204
	v_cvt_pk_bf16_f32 v82, v92, v93
	v_cndmask_b32_e32 v148, v158, v148, vcc
	v_exp_f32_e32 v205, v148
	v_add_f32_e32 v146, v87, v146
	v_add_f32_e32 v146, v88, v146
	v_add_f32_e32 v146, v89, v146
	v_pk_mul_f32 v[94:95], v[94:95], v[204:205]
	v_add_f32_e32 v146, v90, v146
	v_cvt_pk_bf16_f32 v83, v94, v95
	v_add_f32_e32 v146, v91, v146
	v_add_f32_e32 v146, v92, v146
	v_mfma_f32_32x32x16_bf16 v[64:79], v[80:83], v[96:99], v[64:79]
	v_add_f32_e32 v146, v93, v146
	v_add_f32_e32 v146, v94, v146
	v_add_f32_e32 v146, v95, v146

; #define LAS __attribute__((address_space(3)))
; DI unsigned pk2(float a, float b) { f32x2 v = {a, b}; return __builtin_bit_cast(unsigned, __builtin_convertvector(v, bf16v2)); }
; #define MFMA32(a, b, c) __builtin_amdgcn_mfma_f32_32x32x16_bf16((a), (b), (c), 0, 0, 0)
; #define LFENCE() asm volatile("s_waitcnt lgkmcnt(0)" ::: "memory")
; #define DOT2(a, b, c) dot2_bf16((a), (b), (c))
; DI bf16x8 pack_step(const f32x16& x, int s) { u32x4 p = {pk2(x[8 * s], x[8 * s + 1]), pk2(x[8 * s + 2], x[8 * s + 3]), pk2(x[8 * s + 4], x[8 * s + 5]), pk2(x[8 * s + 6], x[8 * s + 7])}; return __builtin_bit_cast(bf16x8, p); }
; DI bf16x8 ldsfrag(const LAS unsigned char* buf, unsigned o) { const s16x4 lo = *(const LAS s16x4*)(buf + o), hi = *(const LAS s16x4*)(buf + (o ^ 16u)); return __builtin_shufflevector(lo, hi, 0, 1, 2, 3, 4, 5, 6, 7); }
; DI void scan_phase(const Args& A, LAS unsigned char* lds, int wv) {
;     ...
;                 const unsigned qo = qro + tb * 8192u;
;                 f32x16 ha;
; #pragma unroll
;                 for (int i = 0; i < 16; ++i) ha[i] = 0.f;
;                 float qnv = 0.f;
; #pragma unroll
;                 for (int kk = 0; kk < 8; ++kk) {
;                     const bf16x8 qa = ldsfrag(Qb, qo + (((2u * kk) ^ xr) << 4));
;                     ha = MFMA32(qa, pack_step(cacc[kk >> 1], kk & 1), ha);
;                     { const u32x2 nb0 = *(const LAS u32x2*)(nbh + 8 * kk), nb1 = *(const LAS u32x2*)(nbh + 8 * kk + 4); const u32x4 qw = __builtin_bit_cast(u32x4, qa);
;                       qnv = DOT2(qw.x, nb0.x, qnv); qnv = DOT2(qw.y, nb0.y, qnv); qnv = DOT2(qw.z, nb1.x, qnv); qnv = DOT2(qw.w, nb1.y, qnv); }
;                 }
;                 qnv += __shfl_xor(qnv, 32);
; #pragma unroll
;                 for (int g = 0; g < 4; ++g) { const f32x4 av = *(const LAS f32x4*)(wh + 128 + 32 * tb + 8 * g);
; #pragma unroll
;                     for (int q = 0; q < 4; ++q) ha[4 * g + q] *= av[q]; }
;                 const float pmt = wr[64 + 32 * tb];
;     ...
;                 LFENCE();
; #pragma unroll
;                 for (int g = 0; g < 4; ++g) { const f32x4 rv = *(const LAS f32x4*)(wh + 320 + 32 * tb + 8 * g);
; #pragma unroll
;                     for (int q = 0; q < 4; ++q) { const int tc = 32 * tb + q + 8 * g;
;                         *(LAS unsigned short*)(hb + tc * 64) = (unsigned short)(pk2(ha[4 * g + q] * rv[q], 0.f) & 0xffffu); } }
.LBB0_1233:
	s_or_b64 exec, exec, s[8:9]
	s_waitcnt lgkmcnt(0)
	ds_read_b128 v[80:83], v174 offset:1280
	ds_read_b128 v[84:87], v174 offset:1312
	v_lshlrev_b32_e32 v88, 1, v164
	v_lshl_add_u32 v89, v192, 6, s47
	v_add_u32_e32 v146, v89, v88
	s_waitcnt lgkmcnt(1)
	v_mul_f32_e32 v64, v64, v80
	v_cvt_pk_bf16_f32 v64, v64, s0
	ds_write_b16 v146, v64 offset:2560
	v_mul_f32_e32 v64, v65, v81
	v_cvt_pk_bf16_f32 v64, v64, s0
	ds_write_b16 v146, v64 offset:2624
	v_mul_f32_e32 v64, v66, v82
	v_cvt_pk_bf16_f32 v64, v64, s0
	ds_write_b16 v146, v64 offset:2688
	v_mul_f32_e32 v64, v67, v83
	v_cvt_pk_bf16_f32 v64, v64, s0
	ds_write_b16 v146, v64 offset:2752
	s_waitcnt lgkmcnt(4)
	v_mul_f32_e32 v64, v68, v84
	v_cvt_pk_bf16_f32 v64, v64, s0
	ds_write_b16 v146, v64 offset:3072
	v_mul_f32_e32 v64, v69, v85
	v_cvt_pk_bf16_f32 v64, v64, s0
	ds_write_b16 v146, v64 offset:3136
	v_mul_f32_e32 v64, v70, v86
	v_cvt_pk_bf16_f32 v64, v64, s0
	ds_write_b16 v146, v64 offset:3200
	ds_read_b128 v[64:67], v174 offset:1344
	v_mul_f32_e32 v68, v71, v87
	v_cvt_pk_bf16_f32 v68, v68, s0
	ds_write_b16 v146, v68 offset:3264
	ds_read_b128 v[68:71], v174 offset:1376
	s_waitcnt lgkmcnt(2)
	v_mul_f32_e32 v64, v72, v64
	v_cvt_pk_bf16_f32 v64, v64, s0
	ds_write_b16 v146, v64 offset:3584
	v_mul_f32_e32 v64, v73, v65
	v_cvt_pk_bf16_f32 v64, v64, s0
	ds_write_b16 v146, v64 offset:3648
	v_mul_f32_e32 v64, v74, v66
	v_cvt_pk_bf16_f32 v64, v64, s0
	ds_write_b16 v146, v64 offset:3712
	v_mul_f32_e32 v64, v75, v67
	v_cvt_pk_bf16_f32 v64, v64, s0
	ds_write_b16 v146, v64 offset:3776
	s_waitcnt lgkmcnt(4)
	v_mul_f32_e32 v64, v76, v68
	v_cvt_pk_bf16_f32 v64, v64, s0
	ds_write_b16 v146, v64 offset:4096
	v_mul_f32_e32 v64, v77, v69
	v_cvt_pk_bf16_f32 v64, v64, s0
	ds_write_b16 v146, v64 offset:4160
	v_mul_f32_e32 v64, v78, v70
	v_cvt_pk_bf16_f32 v64, v64, s0
	ds_write_b16 v146, v64 offset:4224
	v_mul_f32_e32 v64, v79, v71
	v_cvt_pk_bf16_f32 v64, v64, s0
	ds_write_b16 v146, v64 offset:4288
	v_add_u32_e32 v64, v193, v194
	v_add_u32_e32 v148, s10, v64
	v_bitop3_b32 v64, v203, 16, v194 bitop3:0x36
	v_add_u32_e32 v149, s10, v64
	ds_read_b64 v[80:81], v148 offset:8192
	ds_read_b64 v[82:83], v149
	ds_read2_b64 v[84:87], v170 offset1:2
	ds_read2_b64 v[88:91], v170 offset0:4 offset1:6
	s_waitcnt lgkmcnt(2)
	v_mfma_f32_32x32x16_bf16 v[64:79], v[80:83], v[112:115], 0
	v_mov_b32_e32 v113, v145
	s_waitcnt lgkmcnt(1)
	v_dot2c_f32_bf16 v113, v80, v84
	v_add_u32_e32 v80, v193, v195
	v_dot2c_f32_bf16 v113, v81, v85
	v_add_u32_e32 v202, s10, v80
	v_dot2c_f32_bf16 v113, v82, v86
	v_bitop3_b32 v82, v203, 16, v195 bitop3:0x36
	v_add_u32_e32 v195, s10, v82
	v_dot2c_f32_bf16 v113, v83, v87
	ds_read_b64 v[80:81], v202 offset:8192
	ds_read_b64 v[82:83], v195
	s_waitcnt lgkmcnt(1)
	v_dot2c_f32_bf16 v113, v80, v88
	s_waitcnt lgkmcnt(0)
	v_mfma_f32_32x32x16_bf16 v[64:79], v[80:83], v[116:119], v[64:79]
	v_dot2c_f32_bf16 v113, v81, v89
	v_add_u32_e32 v80, v193, v196
	v_dot2c_f32_bf16 v113, v82, v90
	v_bitop3_b32 v82, v203, 16, v196 bitop3:0x36
	v_add_u32_e32 v194, s10, v80
	v_add_u32_e32 v192, s10, v82
	v_dot2c_f32_bf16 v113, v83, v91
	ds_read_b64 v[80:81], v194 offset:8192
	ds_read_b64 v[82:83], v192
	ds_read2_b64 v[84:87], v170 offset0:8 offset1:10
	s_waitcnt lgkmcnt(0)
	v_dot2c_f32_bf16 v113, v80, v84
	v_mfma_f32_32x32x16_bf16 v[64:79], v[80:83], v[120:123], v[64:79]
	v_dot2c_f32_bf16 v113, v81, v85
	v_add_u32_e32 v80, v193, v197
	v_dot2c_f32_bf16 v113, v82, v86
	v_bitop3_b32 v82, v203, 16, v197 bitop3:0x36
	v_add_u32_e32 v147, s10, v80
	v_add_u32_e32 v123, s10, v82
	v_dot2c_f32_bf16 v113, v83, v87
	ds_read_b64 v[80:81], v147 offset:8192
	ds_read_b64 v[82:83], v123
	ds_read2_b64 v[84:87], v170 offset0:12 offset1:14
	s_waitcnt lgkmcnt(0)
	v_dot2c_f32_bf16 v113, v80, v84
	v_mfma_f32_32x32x16_bf16 v[64:79], v[80:83], v[124:127], v[64:79]
	v_dot2c_f32_bf16 v113, v81, v85
	v_add_u32_e32 v80, v193, v198
	v_dot2c_f32_bf16 v113, v82, v86
	v_bitop3_b32 v82, v203, 16, v198 bitop3:0x36
	v_add_u32_e32 v122, s10, v80
	v_add_u32_e32 v121, s10, v82
	v_dot2c_f32_bf16 v113, v83, v87
	ds_read_b64 v[80:81], v122 offset:8192
	ds_read_b64 v[82:83], v121
	ds_read2_b64 v[84:87], v170 offset0:16 offset1:18
	s_waitcnt lgkmcnt(0)
	v_dot2c_f32_bf16 v113, v80, v84
	v_mfma_f32_32x32x16_bf16 v[64:79], v[80:83], v[128:131], v[64:79]
	v_dot2c_f32_bf16 v113, v81, v85
	v_add_u32_e32 v80, v193, v199
	v_dot2c_f32_bf16 v113, v82, v86
	v_bitop3_b32 v82, v203, 16, v199 bitop3:0x36
	v_add_u32_e32 v120, s10, v80
	v_add_u32_e32 v119, s10, v82
	v_dot2c_f32_bf16 v113, v83, v87
	ds_read_b64 v[80:81], v120 offset:8192
	ds_read_b64 v[82:83], v119
	ds_read2_b64 v[84:87], v170 offset0:20 offset1:22
	s_waitcnt lgkmcnt(0)
	v_dot2c_f32_bf16 v113, v80, v84
	v_mfma_f32_32x32x16_bf16 v[64:79], v[80:83], v[132:135], v[64:79]
	v_dot2c_f32_bf16 v113, v81, v85
	v_add_u32_e32 v80, v193, v200
	v_dot2c_f32_bf16 v113, v82, v86
	v_bitop3_b32 v82, v203, 16, v200 bitop3:0x36
	v_add_u32_e32 v118, s10, v80
	v_add_u32_e32 v117, s10, v82
	v_dot2c_f32_bf16 v113, v83, v87
	ds_read_b64 v[80:81], v118 offset:8192
	ds_read_b64 v[82:83], v117
	ds_read2_b64 v[84:87], v170 offset0:24 offset1:26
	s_waitcnt lgkmcnt(0)
	v_dot2c_f32_bf16 v113, v80, v84
	v_mfma_f32_32x32x16_bf16 v[64:79], v[80:83], v[136:139], v[64:79]
	v_dot2c_f32_bf16 v113, v81, v85
	v_add_u32_e32 v80, v193, v201
	v_dot2c_f32_bf16 v113, v82, v86
	v_bitop3_b32 v82, v203, 16, v201 bitop3:0x36
	v_add_u32_e32 v114, s10, v80
	v_add_u32_e32 v112, s10, v82
	v_dot2c_f32_bf16 v113, v83, v87
	ds_read_b64 v[80:81], v114 offset:8192
	ds_read_b64 v[82:83], v112
	s_waitcnt lgkmcnt(0)
	v_mfma_f32_32x32x16_bf16 v[64:79], v[80:83], v[140:143], v[64:79]
	ds_read2_b64 v[84:87], v170 offset0:28 offset1:30
	s_waitcnt lgkmcnt(0)
	v_dot2c_f32_bf16 v113, v80, v84
	v_or_b32_e32 v116, 32, v164
	v_dot2c_f32_bf16 v113, v81, v85
	s_nop 0
	v_dot2c_f32_bf16 v113, v82, v86
	s_nop 0
	v_dot2c_f32_bf16 v113, v83, v87
	ds_read_b128 v[80:83], v174 offset:640
	ds_read_b128 v[84:87], v174 offset:672
	ds_read_b128 v[88:91], v174 offset:704
	ds_read_b128 v[92:95], v174 offset:736
	ds_bpermute_b32 v115, v169, v113
	ds_read_b32 v124, v168 offset:384
	s_waitcnt lgkmcnt(5)
	v_pk_mul_f32 v[64:65], v[64:65], v[80:81]
	v_xor_b32_e32 v80, 31, v164
	v_cndmask_b32_e64 v80, v80, v116, s[4:5]
	s_waitcnt lgkmcnt(2)
	v_pk_mul_f32 v[78:79], v[78:79], v[94:95]
	v_pk_mul_f32 v[76:77], v[76:77], v[92:93]
	v_pk_mul_f32 v[74:75], v[74:75], v[90:91]
	v_pk_mul_f32 v[72:73], v[72:73], v[88:89]
	v_pk_mul_f32 v[70:71], v[70:71], v[86:87]
	v_pk_mul_f32 v[68:69], v[68:69], v[84:85]
	v_pk_mul_f32 v[66:67], v[66:67], v[82:83]
	v_sub_u32_e32 v125, v80, v175
	s_andn2_b64 vcc, exec, s[4:5]
	s_cbranch_vccnz .LBB0_1235
; #define LAS __attribute__((address_space(3)))
; #define MFMA32(a, b, c) __builtin_amdgcn_mfma_f32_32x32x16_bf16((a), (b), (c), 0, 0, 0)
; DI bf16x8 pack_step(const f32x16& x, int s) { u32x4 p = {pk2(x[8 * s], x[8 * s + 1]), pk2(x[8 * s + 2], x[8 * s + 3]), pk2(x[8 * s + 4], x[8 * s + 5]), pk2(x[8 * s + 6], x[8 * s + 7])}; return __builtin_bit_cast(bf16x8, p); }
; DI bf16x8 ldsfrag(const LAS unsigned char* buf, unsigned o) { const s16x4 lo = *(const LAS s16x4*)(buf + o), hi = *(const LAS s16x4*)(buf + (o ^ 16u)); return __builtin_shufflevector(lo, hi, 0, 1, 2, 3, 4, 5, 6, 7); }
; DI void scan_phase(const Args& A, LAS unsigned char* lds, int wv) {
;     ...
;                 for (int sb = 0; sb < 2; ++sb) {
;                     __builtin_amdgcn_sched_barrier(0);
;                     if (sb != tb && (dir ? sb < tb : sb > tb)) continue;
;                     const unsigned ko = qro + sb * 8192u;
;                     f32x16 st;
; #pragma unroll
;                     for (int i = 0; i < 16; ++i) st[i] = 0.f;
; #pragma unroll
;                     for (int kk = 0; kk < 8; ++kk) { const unsigned c = ((2u * kk) ^ xr) << 4; st = MFMA32(ldsfrag(Kb, ko + c), ldsfrag(Qb, qo + c), st); }
; #pragma unroll
;                     for (int g = 0; g < 4; ++g) { const f32x4 uv = *(const LAS f32x4*)(wh + 32 * sb + 8 * g);
; #pragma unroll
;                         for (int q = 0; q < 4; ++q) {
;                             const int sc = 32 * sb + q + 8 * g;
;                             const int sp = sbase + sgn * sc;
;                             st[4 * g + q] *= __builtin_amdgcn_exp2f((sp <= tp) ? uv[q] - pmt : -1e30f);
;                             ds += st[4 * g + q];
;                         } }
;                     ha = MFMA32(pack_step(st, 0), vf[2 * sb], ha);
;                     ha = MFMA32(pack_step(st, 1), vf[2 * sb + 1], ha);
	ds_read_b64 v[80:81], v176 offset:16384
	ds_read_b64 v[82:83], v177 offset:16384
	ds_read_b64 v[84:85], v148 offset:8192
	ds_read_b64 v[86:87], v149
	ds_read_b64 v[126:127], v190 offset:16384
	ds_read_b64 v[128:129], v191 offset:16384
	ds_read_b64 v[130:131], v202 offset:8192
	ds_read_b64 v[132:133], v195
	v_cmp_lt_i32_e32 vcc, -1, v125
	s_waitcnt lgkmcnt(4)
	v_mfma_f32_32x32x16_bf16 v[80:95], v[80:83], v[84:87], 0
	ds_read_b64 v[248:249], v188 offset:16384
	ds_read_b64 v[250:251], v189 offset:16384
	ds_read_b64 v[252:253], v194 offset:8192
	ds_read_b64 v[254:255], v192
	s_waitcnt lgkmcnt(4)
	v_mfma_f32_32x32x16_bf16 v[80:95], v[126:129], v[130:133], v[80:95]
	ds_read_b64 v[126:127], v186 offset:16384
	ds_read_b64 v[128:129], v187 offset:16384
	ds_read_b64 v[130:131], v147 offset:8192
	ds_read_b64 v[132:133], v123
	s_waitcnt lgkmcnt(4)
	v_mfma_f32_32x32x16_bf16 v[80:95], v[248:251], v[252:255], v[80:95]
	ds_read_b64 v[248:249], v184 offset:16384
	ds_read_b64 v[250:251], v185 offset:16384
	ds_read_b64 v[252:253], v122 offset:8192
	ds_read_b64 v[254:255], v121
	s_waitcnt lgkmcnt(4)
	v_mfma_f32_32x32x16_bf16 v[80:95], v[126:129], v[130:133], v[80:95]
	ds_read_b64 v[126:127], v182 offset:16384
	ds_read_b64 v[128:129], v183 offset:16384
	ds_read_b64 v[130:131], v120 offset:8192
	ds_read_b64 v[132:133], v119
	s_waitcnt lgkmcnt(4)
	v_mfma_f32_32x32x16_bf16 v[80:95], v[248:251], v[252:255], v[80:95]
	ds_read_b64 v[248:249], v180 offset:16384
	ds_read_b64 v[250:251], v181 offset:16384
	ds_read_b64 v[252:253], v118 offset:8192
	ds_read_b64 v[254:255], v117
	s_waitcnt lgkmcnt(4)
	v_mfma_f32_32x32x16_bf16 v[80:95], v[126:129], v[130:133], v[80:95]
	ds_read_b64 v[126:127], v178 offset:16384
	ds_read_b64 v[128:129], v179 offset:16384
	ds_read_b64 v[130:131], v114 offset:8192
	ds_read_b64 v[132:133], v112
	s_waitcnt lgkmcnt(4)
	v_mfma_f32_32x32x16_bf16 v[80:95], v[248:251], v[252:255], v[80:95]
	s_waitcnt lgkmcnt(0)
	v_mfma_f32_32x32x16_bf16 v[80:95], v[126:129], v[130:133], v[80:95]
	ds_read_b128 v[126:129], v174
	ds_read_b128 v[130:133], v174 offset:32
	s_waitcnt lgkmcnt(1)
	v_sub_f32_e32 v126, v126, v124
	v_cndmask_b32_e32 v126, v158, v126, vcc
	v_sub_f32_e32 v127, v127, v124
	v_cmp_lt_i32_e32 vcc, 0, v125
	v_exp_f32_e32 v126, v126
	s_nop 0
	v_cndmask_b32_e32 v127, v158, v127, vcc
	v_exp_f32_e32 v127, v127
	v_cmp_lt_i32_e32 vcc, 1, v125
	v_pk_mul_f32 v[80:81], v[80:81], v[126:127]
	s_nop 0
	v_add_f32_e32 v126, 0, v80
	v_add_f32_e32 v134, v81, v126
	v_sub_f32_e32 v126, v128, v124
	v_cndmask_b32_e32 v126, v158, v126, vcc
	v_sub_f32_e32 v127, v129, v124
	v_cmp_lt_i32_e32 vcc, 2, v125
	v_exp_f32_e32 v126, v126
	v_cvt_pk_bf16_f32 v80, v80, v81
	v_cndmask_b32_e32 v127, v158, v127, vcc
	v_exp_f32_e32 v127, v127
	v_cmp_lt_i32_e32 vcc, 7, v125
	v_pk_mul_f32 v[82:83], v[82:83], v[126:127]
	s_nop 0
	v_add_f32_e32 v126, v82, v134
	v_add_f32_e32 v128, v83, v126
	s_waitcnt lgkmcnt(0)
	v_sub_f32_e32 v126, v130, v124
	v_cndmask_b32_e32 v126, v158, v126, vcc
	v_sub_f32_e32 v127, v131, v124
	v_cmp_lt_i32_e32 vcc, 8, v125
	v_exp_f32_e32 v126, v126
	v_cvt_pk_bf16_f32 v81, v82, v83
	v_cndmask_b32_e32 v127, v158, v127, vcc
	v_exp_f32_e32 v127, v127
	v_cmp_lt_i32_e32 vcc, 9, v125
	v_pk_mul_f32 v[84:85], v[84:85], v[126:127]
	s_nop 0
	v_add_f32_e32 v126, v84, v128
	v_add_f32_e32 v128, v85, v126
	v_sub_f32_e32 v126, v132, v124
	v_cndmask_b32_e32 v126, v158, v126, vcc
	v_sub_f32_e32 v127, v133, v124
	v_cmp_lt_i32_e32 vcc, 10, v125
	v_exp_f32_e32 v126, v126
	v_cvt_pk_bf16_f32 v82, v84, v85
	v_cndmask_b32_e32 v127, v158, v127, vcc
	v_exp_f32_e32 v127, v127
	v_cmp_lt_i32_e32 vcc, 15, v125
	v_pk_mul_f32 v[86:87], v[86:87], v[126:127]
	s_nop 0
	v_add_f32_e32 v126, v86, v128
	v_add_f32_e32 v132, v87, v126
	ds_read_b128 v[126:129], v174 offset:64
	v_cvt_pk_bf16_f32 v83, v86, v87
	s_waitcnt lgkmcnt(0)
	v_sub_f32_e32 v126, v126, v124
	v_cndmask_b32_e32 v126, v158, v126, vcc
	v_sub_f32_e32 v127, v127, v124
	v_cmp_lt_i32_e32 vcc, 16, v125
	v_exp_f32_e32 v126, v126
	v_mfma_f32_32x32x16_bf16 v[64:79], v[80:83], v[108:111], v[64:79]
	v_cndmask_b32_e32 v127, v158, v127, vcc
	v_exp_f32_e32 v127, v127
	v_cmp_lt_i32_e32 vcc, 17, v125
	v_pk_mul_f32 v[130:131], v[88:89], v[126:127]
	s_nop 0
	v_add_f32_e32 v88, v130, v132
	v_add_f32_e32 v126, v131, v88
	v_sub_f32_e32 v88, v128, v124
	v_cndmask_b32_e32 v88, v158, v88, vcc
	v_sub_f32_e32 v89, v129, v124
	v_cmp_lt_i32_e32 vcc, 18, v125
	v_exp_f32_e32 v88, v88
	v_cvt_pk_bf16_f32 v80, v130, v131
	v_cndmask_b32_e32 v89, v158, v89, vcc
	v_exp_f32_e32 v89, v89
	v_cmp_lt_i32_e32 vcc, 23, v125
	v_pk_mul_f32 v[128:129], v[90:91], v[88:89]
	s_nop 0
	v_add_f32_e32 v88, v128, v126
	v_add_f32_e32 v126, v129, v88
	ds_read_b128 v[88:91], v174 offset:96
	v_cvt_pk_bf16_f32 v81, v128, v129
	s_waitcnt lgkmcnt(0)
	v_sub_f32_e32 v88, v88, v124
	v_cndmask_b32_e32 v88, v158, v88, vcc
	v_sub_f32_e32 v89, v89, v124
	v_cmp_lt_i32_e32 vcc, 24, v125
	v_sub_f32_e32 v90, v90, v124
	v_sub_f32_e32 v91, v91, v124
	v_cndmask_b32_e32 v89, v158, v89, vcc
	v_cmp_lt_i32_e32 vcc, 25, v125
	v_exp_f32_e32 v88, v88
	v_exp_f32_e32 v89, v89
	v_cndmask_b32_e32 v90, v158, v90, vcc
	v_cmp_lt_i32_e32 vcc, 26, v125
	v_exp_f32_e32 v90, v90
	v_pk_mul_f32 v[88:89], v[92:93], v[88:89]
	v_cndmask_b32_e32 v91, v158, v91, vcc
	v_exp_f32_e32 v91, v91
	v_cvt_pk_bf16_f32 v82, v88, v89
	v_add_f32_e32 v92, v88, v126
	v_add_f32_e32 v92, v89, v92
	v_pk_mul_f32 v[90:91], v[94:95], v[90:91]
	s_nop 0
	v_cvt_pk_bf16_f32 v83, v90, v91
	v_add_f32_e32 v92, v90, v92
	v_add_f32_e32 v126, v91, v92
	v_mfma_f32_32x32x16_bf16 v[64:79], v[80:83], v[104:107], v[64:79]
	s_branch .LBB0_1236

; #define LAS __attribute__((address_space(3)))
; DI unsigned pk2(float a, float b) { f32x2 v = {a, b}; return __builtin_bit_cast(unsigned, __builtin_convertvector(v, bf16v2)); }
; #define LFENCE() asm volatile("s_waitcnt lgkmcnt(0)" ::: "memory")
; DI float bfs(short h) { return __uint_as_float(((unsigned)(unsigned short)h) << 16); }
; DI void scan_phase(const Args& A, LAS unsigned char* lds, int wv) {
;     ...
;             LFENCE();
;             {
;                 bf16_t* hp = Hout + (size_t)(pos0 + lj) * DM;
;                 const LAS unsigned char* hrow = hst + lj * 64;
; #pragma unroll
;                 for (int q = 0; q < 4; ++q) *(u32x4*)(hp + 8 * q) = *(const LAS u32x4*)(hrow + 16 * q);
;             }
;             __builtin_amdgcn_sched_barrier(0);
;             bf16x8 vfw[4];
; #pragma unroll
;             for (int kk = 0; kk < 4; ++kk) {
;                 const f32x4 w0 = *(const LAS f32x4*)(wh + 256 + 16 * kk), w1 = *(const LAS f32x4*)(wh + 256 + 16 * kk + 8);
;                 u32x4 p = {pk2(bfs(vf[kk][0]) * w0[0], bfs(vf[kk][1]) * w0[1]), pk2(bfs(vf[kk][2]) * w0[2], bfs(vf[kk][3]) * w0[3]),
;                            pk2(bfs(vf[kk][4]) * w1[0], bfs(vf[kk][5]) * w1[1]), pk2(bfs(vf[kk][6]) * w1[2], bfs(vf[kk][7]) * w1[3])};
;                 vfw[kk] = __builtin_bit_cast(bf16x8, p);
;             }
; #pragma unroll
;             for (int db = 0; db < 4; ++db) {
; #pragma unroll
;                 for (int i = 0; i < 16; ++i) cacc[db][i] *= decay;
.LBB0_1238:
	s_or_b64 exec, exec, s[8:9]
	s_waitcnt lgkmcnt(0)
	ds_read_b128 v[80:83], v174 offset:1408
	v_sub_f32_e32 v84, v171, v166
	v_mul_f32_e32 v88, 0x3fb8aa3b, v84
	ds_read_b128 v[84:87], v174 offset:1440
	v_exp_f32_e32 v112, v88
	s_waitcnt lgkmcnt(1)
	s_nop 1
	v_mul_f32_e32 v64, v64, v80
	v_cvt_pk_bf16_f32 v64, v64, s0
	ds_write_b16 v146, v64 offset:4608
	v_mul_f32_e32 v64, v65, v81
	v_cvt_pk_bf16_f32 v64, v64, s0
	ds_write_b16 v146, v64 offset:4672
	v_mul_f32_e32 v64, v66, v82
	v_cvt_pk_bf16_f32 v64, v64, s0
	ds_write_b16 v146, v64 offset:4736
	v_mul_f32_e32 v64, v67, v83
	v_cvt_pk_bf16_f32 v64, v64, s0
	ds_write_b16 v146, v64 offset:4800
	s_waitcnt lgkmcnt(4)
	v_mul_f32_e32 v64, v68, v84
	v_cvt_pk_bf16_f32 v64, v64, s0
	ds_write_b16 v146, v64 offset:5120
	v_mul_f32_e32 v64, v69, v85
	v_cvt_pk_bf16_f32 v64, v64, s0
	ds_write_b16 v146, v64 offset:5184
	v_mul_f32_e32 v64, v70, v86
	v_cvt_pk_bf16_f32 v64, v64, s0
	ds_write_b16 v146, v64 offset:5248
	ds_read_b128 v[64:67], v174 offset:1472
	v_mul_f32_e32 v68, v71, v87
	v_cvt_pk_bf16_f32 v68, v68, s0
	ds_write_b16 v146, v68 offset:5312
	ds_read_b128 v[68:71], v174 offset:1504
	s_waitcnt lgkmcnt(2)
	v_mul_f32_e32 v64, v72, v64
	v_cvt_pk_bf16_f32 v64, v64, s0
	ds_write_b16 v146, v64 offset:5632
	v_mul_f32_e32 v64, v73, v65
	v_cvt_pk_bf16_f32 v64, v64, s0
	ds_write_b16 v146, v64 offset:5696
	v_mul_f32_e32 v64, v74, v66
	v_cvt_pk_bf16_f32 v64, v64, s0
	ds_write_b16 v146, v64 offset:5760
	v_mul_f32_e32 v64, v75, v67
	v_cvt_pk_bf16_f32 v64, v64, s0
	ds_write_b16 v146, v64 offset:5824
	s_waitcnt lgkmcnt(4)
	v_mul_f32_e32 v64, v76, v68
	v_cvt_pk_bf16_f32 v64, v64, s0
	ds_write_b16 v146, v64 offset:6144
	v_mul_f32_e32 v64, v77, v69
	v_cvt_pk_bf16_f32 v64, v64, s0
	ds_write_b16 v146, v64 offset:6208
	v_mul_f32_e32 v64, v78, v70
	v_cvt_pk_bf16_f32 v64, v64, s0
	ds_write_b16 v146, v64 offset:6272
	v_mul_f32_e32 v64, v79, v71
	v_cvt_pk_bf16_f32 v64, v64, s0
	ds_write_b16 v146, v64 offset:6336
	v_add_u32_e32 v64, s74, v173
	s_waitcnt lgkmcnt(0)
	v_ashrrev_i32_e32 v65, 31, v64
	v_lshl_add_u32 v76, v173, 6, s47
	v_lshlrev_b64 v[80:81], 12, v[64:65]
	ds_read_b128 v[64:67], v76 offset:2560
	ds_read_b128 v[68:71], v76 offset:2576
	ds_read_b128 v[72:75], v76 offset:2592
	ds_read_b128 v[76:79], v76 offset:2608
	v_lshl_add_u64 v[80:81], s[70:71], 0, v[80:81]
	s_waitcnt lgkmcnt(3)
	global_store_dwordx4 v[80:81], v[64:67], off
	s_waitcnt lgkmcnt(2)
	global_store_dwordx4 v[80:81], v[68:71], off offset:16
	s_waitcnt lgkmcnt(1)
	global_store_dwordx4 v[80:81], v[72:75], off offset:32
	s_waitcnt lgkmcnt(0)
	global_store_dwordx4 v[80:81], v[76:79], off offset:48
	ds_read_b128 v[64:67], v174 offset:1024
	ds_read_b128 v[68:71], v174 offset:1056
	v_and_b32_e32 v73, 0xffff0000, v108
	v_lshlrev_b32_e32 v72, 16, v108
	v_and_b32_e32 v81, 0xffff0000, v100
	s_waitcnt lgkmcnt(1)
	v_pk_mul_f32 v[64:65], v[64:65], v[72:73]
	v_and_b32_e32 v73, 0xffff0000, v109
	v_lshlrev_b32_e32 v72, 16, v109
	v_pk_mul_f32 v[66:67], v[66:67], v[72:73]
	v_cvt_pk_bf16_f32 v64, v64, v65
	v_cvt_pk_bf16_f32 v65, v66, v67
	v_and_b32_e32 v67, 0xffff0000, v110
	v_lshlrev_b32_e32 v66, 16, v110
	s_waitcnt lgkmcnt(0)
	v_pk_mul_f32 v[66:67], v[68:69], v[66:67]
	v_and_b32_e32 v69, 0xffff0000, v111
	v_lshlrev_b32_e32 v68, 16, v111
	v_pk_mul_f32 v[68:69], v[70:71], v[68:69]
	v_cvt_pk_bf16_f32 v66, v66, v67
	v_cvt_pk_bf16_f32 v67, v68, v69
	ds_read_b128 v[68:71], v174 offset:1088
	ds_read_b128 v[74:77], v174 offset:1120
	v_and_b32_e32 v73, 0xffff0000, v104
	v_lshlrev_b32_e32 v72, 16, v104
	v_lshlrev_b32_e32 v80, 16, v100
	s_waitcnt lgkmcnt(1)
	v_pk_mul_f32 v[68:69], v[68:69], v[72:73]
	v_and_b32_e32 v85, 0xffff0000, v96
	v_cvt_pk_bf16_f32 v72, v68, v69
	v_and_b32_e32 v69, 0xffff0000, v105
	v_lshlrev_b32_e32 v68, 16, v105
	v_pk_mul_f32 v[68:69], v[70:71], v[68:69]
	v_lshlrev_b32_e32 v84, 16, v96
	v_cvt_pk_bf16_f32 v73, v68, v69
	v_and_b32_e32 v69, 0xffff0000, v106
	v_lshlrev_b32_e32 v68, 16, v106
	s_waitcnt lgkmcnt(0)
	v_pk_mul_f32 v[68:69], v[74:75], v[68:69]
	v_lshlrev_b32_e32 v92, 3, v172
	v_cvt_pk_bf16_f32 v74, v68, v69
	v_and_b32_e32 v69, 0xffff0000, v107
	v_lshlrev_b32_e32 v68, 16, v107
	v_pk_mul_f32 v[68:69], v[76:77], v[68:69]
	v_lshl_or_b32 v100, v164, 7, v144
	v_cvt_pk_bf16_f32 v75, v68, v69
	ds_read_b128 v[68:71], v174 offset:1152
	ds_read_b128 v[76:79], v174 offset:1184
	v_mov_b32_e32 v96, v145
	v_pk_mul_f32 v[14:15], v[14:15], v[112:113] op_sel_hi:[1,0]
	v_pk_mul_f32 v[12:13], v[12:13], v[112:113] op_sel_hi:[1,0]
	s_waitcnt lgkmcnt(1)
	v_pk_mul_f32 v[68:69], v[68:69], v[80:81]
	v_and_b32_e32 v81, 0xffff0000, v101
	v_lshlrev_b32_e32 v80, 16, v101
	v_pk_mul_f32 v[70:71], v[70:71], v[80:81]
	v_cvt_pk_bf16_f32 v68, v68, v69
	v_cvt_pk_bf16_f32 v69, v70, v71
	v_and_b32_e32 v71, 0xffff0000, v102
	v_lshlrev_b32_e32 v70, 16, v102
	s_waitcnt lgkmcnt(0)
	v_pk_mul_f32 v[70:71], v[76:77], v[70:71]
	v_and_b32_e32 v77, 0xffff0000, v103
	v_lshlrev_b32_e32 v76, 16, v103
	v_pk_mul_f32 v[76:77], v[78:79], v[76:77]
	v_cvt_pk_bf16_f32 v70, v70, v71
	v_cvt_pk_bf16_f32 v71, v76, v77
	ds_read_b128 v[76:79], v174 offset:1216
	ds_read_b128 v[80:83], v174 offset:1248
	v_pk_mul_f32 v[10:11], v[10:11], v[112:113] op_sel_hi:[1,0]
	v_pk_mul_f32 v[8:9], v[8:9], v[112:113] op_sel_hi:[1,0]
	v_pk_mul_f32 v[6:7], v[6:7], v[112:113] op_sel_hi:[1,0]
	s_waitcnt lgkmcnt(1)
	v_pk_mul_f32 v[76:77], v[76:77], v[84:85]
	v_and_b32_e32 v85, 0xffff0000, v97
	v_lshlrev_b32_e32 v84, 16, v97
	v_pk_mul_f32 v[78:79], v[78:79], v[84:85]
	v_cvt_pk_bf16_f32 v76, v76, v77
	v_cvt_pk_bf16_f32 v77, v78, v79
	v_and_b32_e32 v79, 0xffff0000, v98
	v_lshlrev_b32_e32 v78, 16, v98
	s_waitcnt lgkmcnt(0)
; #define LAS __attribute__((address_space(3)))
; DI unsigned pk2(float a, float b) { f32x2 v = {a, b}; return __builtin_bit_cast(unsigned, __builtin_convertvector(v, bf16v2)); }
; #define MFMA32(a, b, c) __builtin_amdgcn_mfma_f32_32x32x16_bf16((a), (b), (c), 0, 0, 0)
; #define DOT2(a, b, c) dot2_bf16((a), (b), (c))
; DI bf16x8 ldsfrag(const LAS unsigned char* buf, unsigned o) { const s16x4 lo = *(const LAS s16x4*)(buf + o), hi = *(const LAS s16x4*)(buf + (o ^ 16u)); return __builtin_shufflevector(lo, hi, 0, 1, 2, 3, 4, 5, 6, 7); }
; DI void scan_phase(const Args& A, LAS unsigned char* lds, int wv) {
;     ...
;             for (int db = 0; db < 4; ++db) {
; #pragma unroll
;                 for (int i = 0; i < 16; ++i) cacc[db][i] *= decay;
;                 const unsigned to = kro + db * 4096u;
;                 float nadd = 0.f;
; #pragma unroll
;                 for (int kk = 0; kk < 4; ++kk) {
;                     const bf16x8 kv = ldsfrag(KTb, to + (((2u * kk) ^ xd) << 4));
;                     const u32x2 wq0 = *(const LAS u32x2*)(wbh + 8 * kk), wq1 = *(const LAS u32x2*)(wbh + 8 * kk + 4); const u32x4 kw = __builtin_bit_cast(u32x4, kv);
;                     nadd = DOT2(kw.x, wq0.x, nadd); nadd = DOT2(kw.y, wq0.y, nadd); nadd = DOT2(kw.z, wq1.x, nadd); nadd = DOT2(kw.w, wq1.y, nadd);
;                     cacc[db] = MFMA32(kv, vfw[kk], cacc[db]);
;                 }
;                 nadd += __shfl_xor(nadd, 32);
;                 const float nnew = decay * wr[384 + 32 * db] + nadd, npart = __shfl_xor(nnew, 1);
;                 if (h4 == 0) { wr[384 + 32 * db] = nnew; if ((rj & 1) == 0) nbp[(32 * db + rj) >> 1] = pk2(nnew, npart); }
	v_pk_mul_f32 v[78:79], v[80:81], v[78:79]
	v_and_b32_e32 v81, 0xffff0000, v99
	v_lshlrev_b32_e32 v80, 16, v99
	v_pk_mul_f32 v[80:81], v[82:83], v[80:81]
	v_cvt_pk_bf16_f32 v78, v78, v79
	v_cvt_pk_bf16_f32 v79, v80, v81
	v_and_b32_e32 v98, 0x70, v92
	v_and_b32_e32 v80, 1, v172
	v_cmp_eq_u32_e32 vcc, 0, v80
	v_or_b32_e32 v80, v100, v98
	v_add_u32_e32 v81, s10, v80
	ds_read_b64 v[84:85], v81 offset:32768
	v_xad_u32 v80, v80, 16, s10
	ds_read_b64 v[86:87], v80 offset:32768
	ds_read2_b64 v[88:91], v170 offset0:32 offset1:34
	ds_read2_b64 v[80:83], v170 offset0:36 offset1:38
	s_waitcnt lgkmcnt(1)
	v_dot2c_f32_bf16 v96, v84, v88
	v_pk_mul_f32 v[4:5], v[4:5], v[112:113] op_sel_hi:[1,0]
	v_pk_mul_f32 v[2:3], v[2:3], v[112:113] op_sel_hi:[1,0]
	v_pk_mul_f32 v[0:1], v[0:1], v[112:113] op_sel_hi:[1,0]
	v_dot2c_f32_bf16 v96, v85, v89
	v_bitop3_b32 v102, v92, 32, v159 bitop3:0x6c
	v_dot2c_f32_bf16 v96, v86, v90
	v_bitop3_b32 v101, v92, 64, v159 bitop3:0x6c
	v_mfma_f32_32x32x16_bf16 v[0:15], v[84:87], v[64:67], v[0:15]
	v_or_b32_e32 v86, v100, v102
	v_add_u32_e32 v84, s10, v86
	v_xad_u32 v86, v86, 16, s10
	v_dot2c_f32_bf16 v96, v87, v91
	ds_read_b64 v[84:85], v84 offset:32768
	ds_read_b64 v[86:87], v86 offset:32768
	s_waitcnt lgkmcnt(1)
	v_dot2c_f32_bf16 v96, v84, v80
	s_waitcnt lgkmcnt(0)
	v_mfma_f32_32x32x16_bf16 v[0:15], v[84:87], v[72:75], v[0:15]
	v_or_b32_e32 v84, v100, v101
	v_dot2c_f32_bf16 v96, v85, v81
	v_add_u32_e32 v85, s10, v84
	ds_read_b64 v[88:89], v85 offset:32768
	v_dot2c_f32_bf16 v96, v86, v82
	v_xad_u32 v84, v84, 16, s10
	v_dot2c_f32_bf16 v96, v87, v83
	ds_read_b64 v[90:91], v84 offset:32768
	ds_read2_b64 v[84:87], v170 offset0:40 offset1:42
	v_bitop3_b32 v99, v92, s16, v159 bitop3:0x6c
	s_waitcnt lgkmcnt(0)
	v_dot2c_f32_bf16 v96, v88, v84
	v_mfma_f32_32x32x16_bf16 v[0:15], v[88:91], v[68:71], v[0:15]
	v_or_b32_e32 v88, v100, v99
	v_dot2c_f32_bf16 v96, v89, v85
	v_add_u32_e32 v89, s10, v88
	v_dot2c_f32_bf16 v96, v90, v86
	ds_read_b64 v[92:93], v89 offset:32768
	v_xad_u32 v88, v88, 16, s10
	v_dot2c_f32_bf16 v96, v91, v87
	ds_read_b64 v[94:95], v88 offset:32768
	ds_read2_b64 v[88:91], v170 offset0:44 offset1:46
	s_waitcnt lgkmcnt(0)
	v_dot2c_f32_bf16 v96, v92, v88
	s_nop 0
	v_dot2c_f32_bf16 v96, v93, v89
	v_mfma_f32_32x32x16_bf16 v[0:15], v[92:95], v[76:79], v[0:15]
	v_dot2c_f32_bf16 v96, v94, v90
	ds_read_b32 v93, v168 offset:1536
	v_dot2c_f32_bf16 v96, v95, v91
	s_nop 2
	v_mov_b32_e32 v92, v96
	s_nop 1
	v_permlane32_swap_b32_e32 v92, v96
	s_waitcnt lgkmcnt(0)
	v_add_f32_e32 v92, v96, v92
	v_fmac_f32_e32 v92, v112, v93
	s_nop 1
	v_mov_b32_dpp v93, v92 quad_perm:[1,0,3,2] row_mask:0xf bank_mask:0xf
	s_and_saveexec_b64 s[8:9], s[6:7]
	s_cbranch_execz .LBB0_1241
	ds_write_b32 v168, v92 offset:1536
	s_and_b64 exec, exec, vcc
	s_cbranch_execz .LBB0_1241
	s_waitcnt lgkmcnt(1)
	v_cvt_pk_bf16_f32 v92, v92, v93
	v_lshl_add_u32 v93, v164, 1, s47
	ds_write_b32 v93, v92 offset:2048
.LBB0_1241:
	s_or_b64 exec, exec, s[8:9]
	s_waitcnt lgkmcnt(0)
	v_add_u32_e32 v93, v100, v98
	v_add_u32_e32 v105, s10, v93
	v_or_b32_e32 v104, 0x1000, v100
	ds_read_b64 v[106:107], v105 offset:36864
	v_or_b32_e32 v92, v104, v98
	v_xad_u32 v92, v92, 16, s10
	ds_read_b64 v[108:109], v92 offset:32768
	ds_read2_b64 v[92:95], v170 offset0:32 offset1:34
	v_mov_b32_e32 v113, v112
	v_mov_b32_e32 v96, v112
	v_mov_b32_e32 v97, v112
	v_mov_b32_e32 v114, 0
	v_pk_mul_f32 v[30:31], v[30:31], v[96:97]
	v_pk_mul_f32 v[28:29], v[28:29], v[96:97]
	v_pk_mul_f32 v[26:27], v[26:27], v[96:97]
	v_pk_mul_f32 v[24:25], v[24:25], v[96:97]
	v_pk_mul_f32 v[22:23], v[22:23], v[96:97]
	v_pk_mul_f32 v[20:21], v[20:21], v[96:97]
	v_pk_mul_f32 v[18:19], v[18:19], v[96:97]
	v_pk_mul_f32 v[16:17], v[16:17], v[112:113]
	s_waitcnt lgkmcnt(0)
	v_dot2c_f32_bf16 v114, v106, v92
	v_or_b32_e32 v103, v104, v102
	v_dot2c_f32_bf16 v114, v107, v93
	v_xad_u32 v103, v103, 16, s10
	v_mfma_f32_32x32x16_bf16 v[16:31], v[106:109], v[64:67], v[16:31]
	v_add_u32_e32 v106, v100, v102
	v_dot2c_f32_bf16 v114, v108, v94
	v_add_u32_e32 v106, s10, v106
	v_dot2c_f32_bf16 v114, v109, v95
	ds_read_b64 v[108:109], v106 offset:36864
	ds_read_b64 v[110:111], v103 offset:32768
	s_waitcnt lgkmcnt(1)
	v_dot2c_f32_bf16 v114, v108, v80
	v_add_u32_e32 v80, v100, v101
	v_dot2c_f32_bf16 v114, v109, v81
	v_add_u32_e32 v103, s10, v80
	s_waitcnt lgkmcnt(0)
	v_dot2c_f32_bf16 v114, v110, v82
	v_or_b32_e32 v82, v104, v101
	v_xad_u32 v82, v82, 16, s10
	v_dot2c_f32_bf16 v114, v111, v83
	ds_read_b64 v[80:81], v103 offset:36864
	ds_read_b64 v[82:83], v82 offset:32768
	v_mfma_f32_32x32x16_bf16 v[16:31], v[108:111], v[72:75], v[16:31]
	s_waitcnt lgkmcnt(1)
	v_dot2c_f32_bf16 v114, v80, v84
	s_nop 0
	v_dot2c_f32_bf16 v114, v81, v85
	s_waitcnt lgkmcnt(0)
	v_dot2c_f32_bf16 v114, v82, v86
	s_nop 0
	v_dot2c_f32_bf16 v114, v83, v87
	v_mfma_f32_32x32x16_bf16 v[16:31], v[80:83], v[68:71], v[16:31]
	v_or_b32_e32 v82, v104, v99
	v_add_u32_e32 v80, v100, v99
	v_add_u32_e32 v104, s10, v80
	v_xad_u32 v82, v82, 16, s10
	ds_read_b64 v[80:81], v104 offset:36864
	ds_read_b64 v[82:83], v82 offset:32768
	s_waitcnt lgkmcnt(1)
	v_dot2c_f32_bf16 v114, v80, v88
	s_waitcnt lgkmcnt(0)
	v_mfma_f32_32x32x16_bf16 v[16:31], v[80:83], v[76:79], v[16:31]
	v_dot2c_f32_bf16 v114, v81, v89
	ds_read_b32 v81, v168 offset:1664
	v_dot2c_f32_bf16 v114, v82, v90
	s_nop 0
	v_dot2c_f32_bf16 v114, v83, v91
	s_nop 2
	v_mov_b32_e32 v80, v114
	s_nop 1
	v_permlane32_swap_b32_e32 v80, v114
	s_waitcnt lgkmcnt(0)
	v_add_f32_e32 v80, v114, v80
	v_fmac_f32_e32 v80, v112, v81
	s_nop 1
	v_mov_b32_dpp v81, v80 quad_perm:[1,0,3,2] row_mask:0xf bank_mask:0xf
	s_and_saveexec_b64 s[8:9], s[6:7]
	s_cbranch_execz .LBB0_1244
	ds_write_b32 v168, v80 offset:1664
	s_and_b64 exec, exec, vcc
	s_cbranch_execz .LBB0_1244
	s_waitcnt lgkmcnt(1)
	v_cvt_pk_bf16_f32 v80, v80, v81
	v_lshl_add_u32 v81, v116, 1, s47
	ds_write_b32 v81, v80 offset:2048
; #define LAS __attribute__((address_space(3)))
; DI unsigned pk2(float a, float b) { f32x2 v = {a, b}; return __builtin_bit_cast(unsigned, __builtin_convertvector(v, bf16v2)); }
; #define MFMA32(a, b, c) __builtin_amdgcn_mfma_f32_32x32x16_bf16((a), (b), (c), 0, 0, 0)
; #define DOT2(a, b, c) dot2_bf16((a), (b), (c))
; DI bf16x8 ldsfrag(const LAS unsigned char* buf, unsigned o) { const s16x4 lo = *(const LAS s16x4*)(buf + o), hi = *(const LAS s16x4*)(buf + (o ^ 16u)); return __builtin_shufflevector(lo, hi, 0, 1, 2, 3, 4, 5, 6, 7); }
; DI void scan_phase(const Args& A, LAS unsigned char* lds, int wv) {
;     ...
;             for (int db = 0; db < 4; ++db) {
; #pragma unroll
;                 for (int i = 0; i < 16; ++i) cacc[db][i] *= decay;
;                 const unsigned to = kro + db * 4096u;
;                 float nadd = 0.f;
; #pragma unroll
;                 for (int kk = 0; kk < 4; ++kk) {
;                     const bf16x8 kv = ldsfrag(KTb, to + (((2u * kk) ^ xd) << 4));
;                     const u32x2 wq0 = *(const LAS u32x2*)(wbh + 8 * kk), wq1 = *(const LAS u32x2*)(wbh + 8 * kk + 4); const u32x4 kw = __builtin_bit_cast(u32x4, kv);
;                     nadd = DOT2(kw.x, wq0.x, nadd); nadd = DOT2(kw.y, wq0.y, nadd); nadd = DOT2(kw.z, wq1.x, nadd); nadd = DOT2(kw.w, wq1.y, nadd);
;                     cacc[db] = MFMA32(kv, vfw[kk], cacc[db]);
;                 }
;                 nadd += __shfl_xor(nadd, 32);
;                 const float nnew = decay * wr[384 + 32 * db] + nadd, npart = __shfl_xor(nnew, 1);
;                 if (h4 == 0) { wr[384 + 32 * db] = nnew; if ((rj & 1) == 0) nbp[(32 * db + rj) >> 1] = pk2(nnew, npart); }
;             }
.LBB0_1244:
	s_or_b64 exec, exec, s[8:9]
	v_pk_mul_f32 v[46:47], v[46:47], v[96:97]
	v_pk_mul_f32 v[44:45], v[44:45], v[96:97]
	v_pk_mul_f32 v[42:43], v[42:43], v[96:97]
	v_pk_mul_f32 v[40:41], v[40:41], v[96:97]
	v_pk_mul_f32 v[38:39], v[38:39], v[96:97]
	v_pk_mul_f32 v[36:37], v[36:37], v[96:97]
	v_pk_mul_f32 v[34:35], v[34:35], v[96:97]
	v_or_b32_e32 v96, 0x2000, v100
	v_or_b32_e32 v82, v96, v98
	v_xad_u32 v82, v82, 16, s10
	s_waitcnt lgkmcnt(0)
	ds_read_b64 v[80:81], v105 offset:40960
	ds_read_b64 v[88:89], v106 offset:40960
	ds_read_b64 v[82:83], v82 offset:32768
	v_mov_b32_e32 v97, 0
	v_pk_mul_f32 v[32:33], v[32:33], v[112:113]
	s_waitcnt lgkmcnt(2)
	v_dot2c_f32_bf16 v97, v80, v92
	s_nop 0
	v_dot2c_f32_bf16 v97, v81, v93
	s_waitcnt lgkmcnt(0)
	v_mfma_f32_32x32x16_bf16 v[32:47], v[80:83], v[64:67], v[32:47]
	v_or_b32_e32 v80, v96, v102
	v_dot2c_f32_bf16 v97, v82, v94
	v_xad_u32 v80, v80, 16, s10
	v_dot2c_f32_bf16 v97, v83, v95
	ds_read_b64 v[90:91], v80 offset:32768
	ds_read2_b64 v[84:87], v170 offset0:36 offset1:38
	ds_read2_b64 v[80:83], v170 offset0:40 offset1:42
	s_waitcnt lgkmcnt(1)
	v_dot2c_f32_bf16 v97, v88, v84
	s_nop 0
	v_dot2c_f32_bf16 v97, v89, v85
	v_mfma_f32_32x32x16_bf16 v[32:47], v[88:91], v[72:75], v[32:47]
	v_dot2c_f32_bf16 v97, v90, v86
	v_or_b32_e32 v90, v96, v101
	v_xad_u32 v90, v90, 16, s10
	v_dot2c_f32_bf16 v97, v91, v87
	ds_read_b64 v[88:89], v103 offset:40960
	ds_read_b64 v[92:93], v104 offset:40960
	ds_read_b64 v[90:91], v90 offset:32768
	s_waitcnt lgkmcnt(2)
	v_dot2c_f32_bf16 v97, v88, v80
	s_waitcnt lgkmcnt(0)
	v_mfma_f32_32x32x16_bf16 v[32:47], v[88:91], v[68:71], v[32:47]
	v_dot2c_f32_bf16 v97, v89, v81
	v_or_b32_e32 v88, v96, v99
	v_dot2c_f32_bf16 v97, v90, v82
	v_xad_u32 v88, v88, 16, s10
	v_dot2c_f32_bf16 v97, v91, v83
	ds_read_b64 v[94:95], v88 offset:32768
	ds_read2_b64 v[88:91], v170 offset0:44 offset1:46
	s_waitcnt lgkmcnt(0)
	v_dot2c_f32_bf16 v97, v92, v88
	s_nop 0
	v_dot2c_f32_bf16 v97, v93, v89
	v_mfma_f32_32x32x16_bf16 v[32:47], v[92:95], v[76:79], v[32:47]
	v_dot2c_f32_bf16 v97, v94, v90
	ds_read_b32 v93, v168 offset:1792
	v_dot2c_f32_bf16 v97, v95, v91
	s_nop 2
	v_mov_b32_e32 v92, v97
	s_nop 1
	v_permlane32_swap_b32_e32 v92, v97
	s_waitcnt lgkmcnt(0)
	v_add_f32_e32 v92, v97, v92
	v_fmac_f32_e32 v92, v112, v93
	s_nop 1
	v_mov_b32_dpp v93, v92 quad_perm:[1,0,3,2] row_mask:0xf bank_mask:0xf
	s_and_saveexec_b64 s[8:9], s[6:7]
	s_cbranch_execz .LBB0_1247
	ds_write_b32 v168, v92 offset:1792
	s_and_b64 exec, exec, vcc
	s_cbranch_execz .LBB0_1247
	s_waitcnt lgkmcnt(1)
	v_cvt_pk_bf16_f32 v92, v92, v93
	v_lshl_add_u32 v93, v164, 1, s47
	ds_write_b32 v93, v92 offset:2176
.LBB0_1247:
	s_or_b64 exec, exec, s[8:9]
	v_mov_b32_e32 v92, v112
	s_waitcnt lgkmcnt(0)
	v_mov_b32_e32 v93, v112
	v_pk_mul_f32 v[62:63], v[62:63], v[92:93]
	v_pk_mul_f32 v[60:61], v[60:61], v[92:93]
	v_pk_mul_f32 v[58:59], v[58:59], v[92:93]
	v_pk_mul_f32 v[56:57], v[56:57], v[92:93]
	v_pk_mul_f32 v[54:55], v[54:55], v[92:93]
	v_pk_mul_f32 v[52:53], v[52:53], v[92:93]
	v_pk_mul_f32 v[50:51], v[50:51], v[92:93]
	ds_read_b64 v[92:93], v105 offset:45056
	v_or_b32_e32 v96, 0x3000, v100
	v_or_b32_e32 v94, v96, v98
	v_xad_u32 v94, v94, 16, s10
	ds_read_b64 v[94:95], v94 offset:32768
	ds_read2_b64 v[108:111], v170 offset0:32 offset1:34
	v_pk_mul_f32 v[48:49], v[48:49], v[112:113]
	v_mov_b32_e32 v97, 0
	s_waitcnt lgkmcnt(0)
	v_dot2c_f32_bf16 v97, v92, v108
	v_mfma_f32_32x32x16_bf16 v[48:63], v[92:95], v[64:67], v[48:63]
	v_or_b32_e32 v66, v96, v102
	v_xad_u32 v66, v66, 16, s10
	ds_read_b64 v[64:65], v106 offset:45056
	ds_read_b64 v[66:67], v66 offset:32768
	v_dot2c_f32_bf16 v97, v93, v109
	s_nop 0
	v_dot2c_f32_bf16 v97, v94, v110
	s_waitcnt lgkmcnt(0)
	v_mfma_f32_32x32x16_bf16 v[48:63], v[64:67], v[72:75], v[48:63]
	v_dot2c_f32_bf16 v97, v95, v111
	s_nop 0
	v_dot2c_f32_bf16 v97, v64, v84
	s_nop 0
	v_dot2c_f32_bf16 v97, v65, v85
	ds_read_b64 v[64:65], v103 offset:45056
	v_dot2c_f32_bf16 v97, v66, v86
	v_or_b32_e32 v66, v96, v101
	v_xad_u32 v66, v66, 16, s10
	v_dot2c_f32_bf16 v97, v67, v87
	ds_read_b64 v[66:67], v66 offset:32768
	s_waitcnt lgkmcnt(1)
	v_dot2c_f32_bf16 v97, v64, v80
	s_nop 0
	v_dot2c_f32_bf16 v97, v65, v81
	s_waitcnt lgkmcnt(0)
	v_mfma_f32_32x32x16_bf16 v[48:63], v[64:67], v[68:71], v[48:63]
	v_dot2c_f32_bf16 v97, v66, v82
	v_or_b32_e32 v66, v96, v99
	v_xad_u32 v66, v66, 16, s10
	v_dot2c_f32_bf16 v97, v67, v83
	ds_read_b64 v[64:65], v104 offset:45056
	ds_read_b64 v[66:67], v66 offset:32768
	s_waitcnt lgkmcnt(1)
	v_dot2c_f32_bf16 v97, v64, v88
	s_waitcnt lgkmcnt(0)
	v_mfma_f32_32x32x16_bf16 v[48:63], v[64:67], v[76:79], v[48:63]
	v_dot2c_f32_bf16 v97, v65, v89
	ds_read_b32 v65, v168 offset:1920
	v_dot2c_f32_bf16 v97, v66, v90
	s_nop 0
	v_dot2c_f32_bf16 v97, v67, v91
	s_nop 2
	v_mov_b32_e32 v64, v97
	s_nop 1
	v_permlane32_swap_b32_e32 v64, v97
	s_waitcnt lgkmcnt(0)
	v_add_f32_e32 v64, v97, v64
	v_fmac_f32_e32 v64, v112, v65
	s_nop 1
	v_mov_b32_dpp v65, v64 quad_perm:[1,0,3,2] row_mask:0xf bank_mask:0xf
	s_and_saveexec_b64 s[8:9], s[6:7]
	s_cbranch_execz .LBB0_1210
	ds_write_b32 v168, v64 offset:1920
	s_and_b64 exec, exec, vcc
	s_cbranch_execz .LBB0_1210
	s_waitcnt lgkmcnt(1)
	v_cvt_pk_bf16_f32 v64, v64, v65
	v_lshl_add_u32 v65, v164, 1, s47
	ds_write_b32 v65, v64 offset:2240
	s_branch .LBB0_1210
